# attention fused path: LDS operand prefetch carried across pair boundary and mid barrier (partial lgkmcnt instead of drain)
# baseline (speedup 1.0000x reference)
; #define LAS __attribute__((address_space(3)))
; __device__ __forceinline__ int fresh_tid() { int t; asm volatile("v_mov_b32 %0, %1" : "=v"(t) : "v"(threadIdx.x)); return t; }
; template <int TYPE>
; __device__ __forceinline__ void attn_item(const Ctx& a, int b, int h, int qt, LAS unsigned char* lds) {
;     constexpr int DK = TYPE == 0 ? 96 : 64, KLD = DK + 8, KBYTES = 128 * KLD * 2, VLD = 132, VBYTES = 64 * VLD * 2, BUF = KBYTES + VBYTES, NKK = DK / 16;
;     constexpr int NKC = TYPE == 0 ? 3 : 2;
;     const int tid = fresh_tid(), lane = tid & 63, wv = tid >> 6, l32 = lane & 31, hb = lane >> 5;
;     const bf16_t* mr = (const bf16_t*)(a.ws + B_MLA); const bf16_t* pa = (const bf16_t*)(a.ws + B_PROJ); const bf16_t* kro = (const bf16_t*)(a.ws + B_KROPE);
;     bf16_t* br = (bf16_t*)(a.ws + B_BRANCH);
;     const int qrow = qt * 256 + wv * 32 + l32;
;     bf16x8 Q[NKK];
;     {
;         const bf16_t* qp = TYPE == 0 ? mr + (size_t)qrow * MR + h * 96 : pa + (size_t)qrow * PA + C_MQ + h * 64;
; #pragma unroll
;         for (int kk = 0; kk < NKK; ++kk) Q[kk] = *(const bf16x8*)(qp + kk * 16 + hb * 8);
;     }
;     unsigned qmask = 0xffffffffu;
;     if (TYPE == 1) qmask = ((const unsigned*)(a.ws + WS_MASK))[(size_t)h * SEQ + qrow];
;     f32x16 oacc[2];
; #pragma unroll
;     for (int db = 0; db < 2; ++db)
; #pragma unroll
;         for (int r = 0; r < 16; ++r) oacc[db][r] = 0.f;
;     float mrun = 0.f, lrun = 0.f;
;     const int npair = (qt + 1) * 2;
;     u32x4 kreg[NKC], vreg[2];
;     ...
;     AT_LOAD(0); AT_STORE(0);
;     __syncthreads();
.Lat0_entry:
	s_lshr_b32 s47, s12, 4
	s_sub_u32 s47, 31, s47
	s_and_b32 s50, s12, 7
	v_lshrrev_b32 v1, 6, v179
	s_add_u32 s30, s47, 1
	s_lshl_b32 s30, s30, 1
	v_readfirstlane_b32 s51, v1
	v_and_b32 v14, 31, v195
	v_lshrrev_b32 v15, 5, v195
	s_lshl_b32 s8, s47, 8
	s_lshl_b32 s9, s51, 5
	s_add_u32 s8, s8, s9
	v_add_u32 v144, s8, v14
	v_add_u32 v208, s9, v14
	v_lshlrev_b32 v181, 2, v15
	v_sub_u32 v208, v208, v181
	s_mul_i32 s9, s50, 0xc0
	s_add_u32 s56, s16, 0xc8f4200
	s_addc_u32 s57, s17, 0
	s_add_u32 s56, s56, s9
	s_addc_u32 s57, s57, 0
	s_movk_i32 s8, 0xe00
	v_mul_lo_u32 v181, v144, s8
	v_lshl_add_u32 v181, v15, 4, v181
	global_load_dwordx4 v[112:115], v181, s[56:57] offset:0
	global_load_dwordx4 v[116:119], v181, s[56:57] offset:32
	global_load_dwordx4 v[120:123], v181, s[56:57] offset:64
	global_load_dwordx4 v[124:127], v181, s[56:57] offset:96
	global_load_dwordx4 v[128:131], v181, s[56:57] offset:128
	global_load_dwordx4 v[132:135], v181, s[56:57] offset:160
	v_lshrrev_b32 v181, 3, v179
	v_and_b32 v212, 7, v179
	s_lshl_b32 s9, s50, 8
	s_add_u32 s52, s16, 0xc8f4800
	s_addc_u32 s53, s17, 0
	s_add_u32 s52, s52, s9
	s_addc_u32 s53, s53, 0
	s_lshl_b32 s9, s50, 6
	s_add_u32 s54, s16, 0xe4f4200
	s_addc_u32 s55, s17, 0
	s_add_u32 s54, s54, s9
	s_addc_u32 s55, s55, 0
	v_mul_u32_u24 v184, 0xe00, v181
	v_lshl_add_u32 v184, v212, 4, v184
	v_add_u32 v185, 0x38000, v184
	v_lshrrev_b32 v1, 2, v179
	v_and_b32 v188, 3, v179
	v_lshlrev_b32 v186, 9, v1
	v_lshl_add_u32 v186, v188, 4, v186
	v_mul_u32_u24 v201, 0xd0, v1
	v_lshl_add_u32 v201, v188, 4, v201
	v_add_u32 v201, 0x80, v201
	v_mul_u32_u24 v190, 208, v14
	v_lshl_add_u32 v190, v15, 4, v190
	v_mul_u32_u24 v193, 208, v181
	v_lshl_add_u32 v193, v212, 4, v193
	v_and_b32 v1, 2, v181
	v_lshlrev_b32 v1, 5, v1
	v_lshlrev_b32 v188, 4, v212
	v_xor_b32 v1, v1, v188
	v_lshl_add_u32 v200, v181, 7, v1
	v_add_u32 v200, 26624, v200
	v_bfe_u32 v1, v195, 2, 2
	v_lshlrev_b32 v191, 7, v1
	v_bfe_u32 v1, v195, 3, 1
	v_lshl_add_u32 v191, v1, 6, v191
	v_bfe_u32 v1, v195, 4, 1
	v_lshl_add_u32 v191, v1, 5, v191
	v_and_b32 v1, 3, v195
	v_lshl_add_u32 v191, v1, 3, v191
	v_lshl_add_u32 v191, v15, 9, v191
	v_add_u32 v191, 26624, v191
	v_xor_b32 v192, 64, v191
	global_load_dwordx4 v[2:5], v184, s[52:53]
	global_load_dwordx4 v[6:9], v184, s[52:53] offset:128
	global_load_dwordx4 v[10:13], v185, s[52:53]
	global_load_dwordx4 v[136:139], v185, s[52:53] offset:128
	global_load_dwordx4 v[140:143], v186, s[54:55]
	s_add_u32 s52, s52, 0x70000
	s_addc_u32 s53, s53, 0
	s_add_u32 s54, s54, 0x10000
	s_addc_u32 s55, s55, 0
	v_mov_b32 v16, 0
	v_mov_b32 v17, 0
	v_mov_b32 v18, 0
	v_mov_b32 v19, 0
	v_mov_b32 v20, 0
	v_mov_b32 v21, 0
	v_mov_b32 v22, 0
	v_mov_b32 v23, 0
	v_mov_b32 v24, 0
	v_mov_b32 v25, 0
	v_mov_b32 v26, 0
	v_mov_b32 v27, 0
	v_mov_b32 v28, 0
	v_mov_b32 v29, 0
	v_mov_b32 v30, 0
	v_mov_b32 v31, 0
	v_mov_b32 v32, 0
	v_mov_b32 v33, 0
	v_mov_b32 v34, 0
	v_mov_b32 v35, 0
	v_mov_b32 v36, 0
	v_mov_b32 v37, 0
	v_mov_b32 v38, 0
	v_mov_b32 v39, 0
	v_mov_b32 v40, 0
	v_mov_b32 v41, 0
	v_mov_b32 v42, 0
	v_mov_b32 v43, 0
	v_mov_b32 v44, 0
	v_mov_b32 v45, 0
	v_mov_b32 v46, 0
	v_mov_b32 v47, 0
	v_mov_b32 v205, 0
	v_mov_b32 v206, 0
	v_mov_b32 v207, 0x41000000
	s_mov_b64 s[36:37], 0
	s_mov_b32 s26, 0
	s_waitcnt vmcnt(0)
	ds_write_b128 v193, v[2:5]
	ds_write_b128 v193, v[10:13] offset:13312
	ds_write_b128 v200, v[6:9]
	ds_write_b128 v200, v[136:139] offset:8192
	ds_write_b128 v201, v[140:143]
	s_waitcnt lgkmcnt(0)
	global_load_dwordx4 v[2:5], v184, s[52:53]
	global_load_dwordx4 v[6:9], v184, s[52:53] offset:128
	global_load_dwordx4 v[10:13], v185, s[52:53]
	global_load_dwordx4 v[136:139], v185, s[52:53] offset:128
	global_load_dwordx4 v[140:143], v186, s[54:55]
	s_add_u32 s52, s52, 0x70000
	s_addc_u32 s53, s53, 0
	s_add_u32 s54, s54, 0x10000
	s_addc_u32 s55, s55, 0
	s_mov_b32 s8, 0xa800
	v_add_u32 v193, s8, v193
	v_add_u32 v200, s8, v200
	v_add_u32 v201, s8, v201
	s_mov_b32 s12, 0
	s_mov_b32 s13, 1
	s_waitcnt lgkmcnt(0)
	s_barrier
	ds_read_b128 v[146:149], v190 offset:0
	ds_read_b128 v[150:153], v190 offset:6656
	ds_read_b128 v[154:157], v190 offset:32
	ds_read_b128 v[158:161], v190 offset:6688
	ds_read_b128 v[162:165], v190 offset:64
	ds_read_b128 v[166:169], v190 offset:6720
; template <int TYPE>
; __device__ __forceinline__ void attn_item(const Ctx& a, int b, int h, int qt, LAS unsigned char* lds) {
;     ...
; #pragma unroll
;         for (int kk = 0; kk < NKK; ++kk)
; #pragma unroll
;             for (int sub = 0; sub < 2; ++sub)
;                 if (act[sub]) {
; #pragma unroll
;                     for (int kb = 0; kb < 2; ++kb) {
;                         bf16x8 ka = *(const LAS bf16x8*)(Kt + (sub * 64 + kb * 32 + l32) * KLD + kk * 16 + hb * 8);
;                         s[sub][kb] = __builtin_amdgcn_mfma_f32_32x32x16_bf16(ka, Q[kk], s[sub][kb], 0, 0, 0);
;                     }
;                 }
; #pragma unroll
;         for (int sub = 0; sub < 2; ++sub) {
;             if (!act[sub]) continue;
;             const int kt = kp * 2 + sub, kloc = kt - qt * 4;
;             if (kloc >= 0) {
; #pragma unroll
;                 for (int kb = 0; kb < 2; ++kb)
; #pragma unroll
;                     for (int r = 0; r < 16; ++r) { int kabs = kt * 64 + kb * 32 + (r >> 2) * 8 + hb * 4 + (r & 3); if (kabs > qrow) s[sub][kb][r] = -1e30f; }
;             } else if (TYPE == 1) {
;                 if (!((qmask >> (kt >> 2)) & 1u)) {
; #pragma unroll
;                     for (int kb = 0; kb < 2; ++kb)
; #pragma unroll
;                         for (int r = 0; r < 16; ++r) s[sub][kb][r] = -1e30f;
;                 }
;             }
;             float mx = -1e30f;
; #pragma unroll
;             for (int kb = 0; kb < 2; ++kb)
; #pragma unroll
;                 for (int r = 0; r < 16; ++r) mx = fmaxf(mx, s[sub][kb][r]);
;             mx = fmaxf(mx, __shfl_xor(mx, 32));
;             const float delta = mrun - mref;
;             const bool bump = (mx - delta) > 8.f;
;             const bool rare = __builtin_amdgcn_ballot_w64(bump || delta != 0.f) != 0ull;
;             float fpost = 1.f;
;             if (rare) {
;                 const float mnew = bump ? mref + mx : mrun;
;                 const float pre = __builtin_amdgcn_exp2f(delta);
;                 fpost = __builtin_amdgcn_exp2f(mref - mnew);
;                 mrun = mnew;
;                 lrun *= pre;
; #pragma unroll
;                 for (int db = 0; db < 2; ++db)
; #pragma unroll
;                     for (int r = 0; r < 16; ++r) oacc[db][r] *= pre;
;             }
;             float ps = 0.f;
; #pragma unroll
;             for (int kb = 0; kb < 2; ++kb)
; #pragma unroll
.Lat0_loop:
	s_add_u32 s8, s26, 2
	s_cmp_ge_u32 s8, s30
	s_cselect_b32 s57, 1, 0
	s_cmp_eq_u32 s57, 1
	s_cbranch_scc1 .Lat0_gen
	s_cmp_lg_u64 s[36:37], 0
	s_cbranch_scc1 .Lat0_gen
	v_mov_b32 v211, v0
	s_cmp_eq_u32 s12, 2
	s_cselect_b32 s58, 0x1f800, 0
	s_sub_u32 s58, 0xa800, s58
	s_add_u32 s12, s12, 1
	s_cmp_eq_u32 s12, 3
	s_cselect_b32 s12, 0, s12
	s_waitcnt lgkmcnt(5)
	v_mfma_f32_32x32x16_bf16 v[48:63], v[146:149], v[112:115], 0
	ds_read_b128 v[170:173], v190 offset:96
	s_waitcnt lgkmcnt(5)
	v_mfma_f32_32x32x16_bf16 v[64:79], v[150:153], v[112:115], 0
	ds_read_b128 v[174:177], v190 offset:6752
	s_waitcnt lgkmcnt(5)
	v_mfma_f32_32x32x16_bf16 v[48:63], v[154:157], v[116:119], v[48:63]
	ds_read_b128 v[146:149], v190 offset:128
	s_waitcnt lgkmcnt(5)
	v_mfma_f32_32x32x16_bf16 v[64:79], v[158:161], v[116:119], v[64:79]
	ds_read_b128 v[150:153], v190 offset:6784
	s_waitcnt lgkmcnt(5)
	v_mfma_f32_32x32x16_bf16 v[48:63], v[162:165], v[120:123], v[48:63]
	ds_read_b128 v[154:157], v190 offset:160
	s_waitcnt lgkmcnt(5)
	v_mfma_f32_32x32x16_bf16 v[64:79], v[166:169], v[120:123], v[64:79]
	ds_read_b128 v[158:161], v190 offset:6816
	s_waitcnt lgkmcnt(5)
	v_mfma_f32_32x32x16_bf16 v[48:63], v[170:173], v[124:127], v[48:63]
	ds_read_b128 v[162:165], v190 offset:13312
	s_waitcnt lgkmcnt(5)
	v_mfma_f32_32x32x16_bf16 v[64:79], v[174:177], v[124:127], v[64:79]
	ds_read_b128 v[166:169], v190 offset:19968
	s_waitcnt lgkmcnt(5)
	v_mfma_f32_32x32x16_bf16 v[48:63], v[146:149], v[128:131], v[48:63]
	ds_read_b128 v[170:173], v190 offset:13344
	s_waitcnt lgkmcnt(5)
	v_mfma_f32_32x32x16_bf16 v[64:79], v[150:153], v[128:131], v[64:79]
	ds_read_b128 v[174:177], v190 offset:20000
	s_waitcnt lgkmcnt(5)
	v_mfma_f32_32x32x16_bf16 v[48:63], v[154:157], v[132:135], v[48:63]
	ds_read_b128 v[146:149], v190 offset:13376
	s_waitcnt lgkmcnt(5)
	v_mfma_f32_32x32x16_bf16 v[64:79], v[158:161], v[132:135], v[64:79]
	ds_read_b128 v[150:153], v190 offset:20032
	s_waitcnt vmcnt(0)
	s_waitcnt lgkmcnt(5)
	v_mfma_f32_32x32x16_bf16 v[80:95], v[162:165], v[112:115], 0
	ds_read_b128 v[154:157], v190 offset:13408
	s_nop 3
	v_max3_f32 v211, v211, v48, v49
	v_exp_f32 v48, v48
	v_exp_f32 v49, v49
	v_max3_f32 v211, v211, v50, v51
	v_exp_f32 v50, v50
	v_exp_f32 v51, v51
	v_add_f32 v188, v48, v49
	v_cvt_pk_bf16_f32 v48, v48, v49
	s_waitcnt lgkmcnt(5)
	v_mfma_f32_32x32x16_bf16 v[96:111], v[166:169], v[112:115], 0
	ds_write_b128 v193, v[2:5]
	ds_read_b128 v[158:161], v190 offset:20064
	v_max3_f32 v211, v211, v52, v53
	v_exp_f32 v52, v52
	v_exp_f32 v53, v53
	v_add_f32 v188, v188, v50
	v_add_f32 v188, v188, v51
	v_cvt_pk_bf16_f32 v49, v50, v51
	v_max3_f32 v211, v211, v54, v55
	v_exp_f32 v54, v54
	s_waitcnt lgkmcnt(6)
	v_mfma_f32_32x32x16_bf16 v[80:95], v[170:173], v[116:119], v[80:95]
	ds_read_b128 v[162:165], v190 offset:13440
	v_exp_f32 v55, v55
	v_add_f32 v188, v188, v52
	v_add_f32 v188, v188, v53
	v_cvt_pk_bf16_f32 v50, v52, v53
	v_max3_f32 v211, v211, v56, v57
	v_exp_f32 v56, v56
	v_exp_f32 v57, v57
	v_add_f32 v188, v188, v54
	s_waitcnt lgkmcnt(6)
	v_mfma_f32_32x32x16_bf16 v[96:111], v[174:177], v[116:119], v[96:111]
	ds_write_b128 v193, v[10:13] offset:13312
	ds_read_b128 v[166:169], v190 offset:20096
	v_add_f32 v188, v188, v55
	v_cvt_pk_bf16_f32 v51, v54, v55
	v_max3_f32 v211, v211, v58, v59
	v_exp_f32 v58, v58
	v_exp_f32 v59, v59
	v_add_f32 v188, v188, v56
	v_add_f32 v188, v188, v57
	v_cvt_pk_bf16_f32 v52, v56, v57
	s_waitcnt lgkmcnt(7)
	v_mfma_f32_32x32x16_bf16 v[80:95], v[146:149], v[120:123], v[80:95]
	ds_read_b128 v[170:173], v190 offset:13472
	v_max3_f32 v211, v211, v60, v61
	v_exp_f32 v60, v60
	v_exp_f32 v61, v61
	v_add_f32 v188, v188, v58
	v_add_f32 v188, v188, v59
	v_cvt_pk_bf16_f32 v53, v58, v59
	v_max3_f32 v211, v211, v62, v63
	v_exp_f32 v62, v62
	s_waitcnt lgkmcnt(7)
	v_mfma_f32_32x32x16_bf16 v[96:111], v[150:153], v[120:123], v[96:111]
	ds_write_b128 v200, v[6:9]
	ds_read_b128 v[174:177], v190 offset:20128
	v_add_u32 v190, s58, v190
	v_exp_f32 v63, v63
	v_add_f32 v188, v188, v60
	v_add_f32 v188, v188, v61
	v_cvt_pk_bf16_f32 v54, v60, v61
	v_add_f32 v188, v188, v62
	v_add_f32 v188, v188, v63
	v_cvt_pk_bf16_f32 v55, v62, v63
	v_max3_f32 v211, v211, v64, v65
	s_waitcnt lgkmcnt(8)
	v_mfma_f32_32x32x16_bf16 v[80:95], v[154:157], v[124:127], v[80:95]
	ds_read_b64_tr_b16 v[146:147], v191 offset:0
	ds_read_b64_tr_b16 v[148:149], v191 offset:1024
	v_exp_f32 v64, v64
	v_exp_f32 v65, v65
	v_max3_f32 v211, v211, v66, v67
	v_exp_f32 v66, v66
	v_exp_f32 v67, v67
	v_add_f32 v188, v188, v64
	v_add_f32 v188, v188, v65
	v_cvt_pk_bf16_f32 v64, v64, v65
	s_waitcnt lgkmcnt(8)
	v_mfma_f32_32x32x16_bf16 v[96:111], v[158:161], v[124:127], v[96:111]
	ds_write_b128 v200, v[136:139] offset:8192
	ds_read_b64_tr_b16 v[150:151], v192 offset:0
	ds_read_b64_tr_b16 v[152:153], v192 offset:1024
	v_max3_f32 v211, v211, v68, v69
	v_exp_f32 v68, v68
	v_exp_f32 v69, v69
	v_add_f32 v188, v188, v66
	v_add_f32 v188, v188, v67
	v_cvt_pk_bf16_f32 v65, v66, v67
	v_max3_f32 v211, v211, v70, v71
	v_exp_f32 v70, v70
	s_waitcnt lgkmcnt(10)
	v_mfma_f32_32x32x16_bf16 v[80:95], v[162:165], v[128:131], v[80:95]
	ds_read_b64_tr_b16 v[154:155], v191 offset:2048
	ds_read_b64_tr_b16 v[156:157], v191 offset:3072
	v_exp_f32 v71, v71
	v_add_f32 v188, v188, v68
	v_add_f32 v188, v188, v69
	v_cvt_pk_bf16_f32 v66, v68, v69
	v_max3_f32 v211, v211, v72, v73
	v_exp_f32 v72, v72
	v_exp_f32 v73, v73
	v_add_f32 v188, v188, v70
	s_waitcnt lgkmcnt(10)
	v_mfma_f32_32x32x16_bf16 v[96:111], v[166:169], v[128:131], v[96:111]
	ds_write_b128 v201, v[140:143]
	ds_read_b64_tr_b16 v[158:159], v192 offset:2048
	ds_read_b64_tr_b16 v[160:161], v192 offset:3072
	v_add_f32 v188, v188, v71
	v_cvt_pk_bf16_f32 v67, v70, v71
	v_max3_f32 v211, v211, v74, v75
	v_exp_f32 v74, v74
	v_exp_f32 v75, v75
	v_add_f32 v188, v188, v72
	v_add_f32 v188, v188, v73
	v_cvt_pk_bf16_f32 v68, v72, v73
	s_waitcnt lgkmcnt(12)
	v_mfma_f32_32x32x16_bf16 v[80:95], v[170:173], v[132:135], v[80:95]
	ds_read_b64_tr_b16 v[162:163], v191 offset:4096
	ds_read_b64_tr_b16 v[164:165], v191 offset:5120
	v_max3_f32 v211, v211, v76, v77
	v_exp_f32 v76, v76
	v_exp_f32 v77, v77
	v_add_f32 v188, v188, v74
	v_add_f32 v188, v188, v75
	v_cvt_pk_bf16_f32 v69, v74, v75
	v_max3_f32 v211, v211, v78, v79
	v_exp_f32 v78, v78
	s_waitcnt lgkmcnt(12)
	v_mfma_f32_32x32x16_bf16 v[96:111], v[174:177], v[132:135], v[96:111]
	ds_read_b64_tr_b16 v[166:167], v192 offset:4096
	ds_read_b64_tr_b16 v[168:169], v192 offset:5120
	v_exp_f32 v79, v79
	v_add_f32 v188, v188, v76
	v_add_f32 v188, v188, v77
	v_cvt_pk_bf16_f32 v70, v76, v77
	v_add_f32 v188, v188, v78
	v_add_f32 v188, v188, v79
	v_cvt_pk_bf16_f32 v71, v78, v79
	v_add_f32 v206, v206, v188
	s_cmp_eq_u32 s13, 2
	s_cselect_b32 s8, 0x1f800, 0
	s_sub_u32 s8, 0xa800, s8
	s_add_u32 s13, s13, 1
	s_cmp_eq_u32 s13, 3
	s_cselect_b32 s13, 0, s13
	s_waitcnt lgkmcnt(6)
	s_add_u32 s9, s26, 2
	s_cmp_lt_u32 s9, s30
	s_cbranch_scc0 .Lat0_mid1
	global_load_dwordx4 v[2:5], v184, s[52:53]
	global_load_dwordx4 v[6:9], v184, s[52:53] offset:128
	global_load_dwordx4 v[10:13], v185, s[52:53]
	global_load_dwordx4 v[136:139], v185, s[52:53] offset:128
	global_load_dwordx4 v[140:143], v186, s[54:55]
	s_add_u32 s52, s52, 0x70000
	s_addc_u32 s53, s53, 0
	s_add_u32 s54, s54, 0x10000
	s_addc_u32 s55, s55, 0
; template <int TYPE>
; __device__ __forceinline__ void attn_item(const Ctx& a, int b, int h, int qt, LAS unsigned char* lds) {
;     ...
;             float mx = -1e30f;
; #pragma unroll
;             for (int kb = 0; kb < 2; ++kb)
; #pragma unroll
;                 for (int r = 0; r < 16; ++r) mx = fmaxf(mx, s[sub][kb][r]);
;             mx = fmaxf(mx, __shfl_xor(mx, 32));
;             const float delta = mrun - mref;
;             const bool bump = (mx - delta) > 8.f;
;             const bool rare = __builtin_amdgcn_ballot_w64(bump || delta != 0.f) != 0ull;
;             float fpost = 1.f;
;             if (rare) {
;                 const float mnew = bump ? mref + mx : mrun;
;                 const float pre = __builtin_amdgcn_exp2f(delta);
;                 fpost = __builtin_amdgcn_exp2f(mref - mnew);
;                 mrun = mnew;
;                 lrun *= pre;
; #pragma unroll
;                 for (int db = 0; db < 2; ++db)
; #pragma unroll
;                     for (int r = 0; r < 16; ++r) oacc[db][r] *= pre;
;             }
;             float ps = 0.f;
; #pragma unroll
;             for (int kb = 0; kb < 2; ++kb)
; #pragma unroll
;                 for (int r = 0; r < 16; ++r) { float p = __builtin_amdgcn_exp2f(s[sub][kb][r]); s[sub][kb][r] = p; ps += p; }
;             lrun += ps;
; #pragma unroll
;             for (int kb = 0; kb < 2; ++kb)
; #pragma unroll
;                 for (int c = 0; c < 2; ++c) {
;                     bf16x8 pb = pack8(s[sub][kb], c);
; #pragma unroll
;                     for (int db = 0; db < 2; ++db)
;                         oacc[db] = __builtin_amdgcn_mfma_f32_32x32x16_bf16(lds_a2(VT + (db * 32 + l32) * VLD + sub * 64 + kb * 32 + c * 16 + hb * 4), pb, oacc[db], 0, 0, 0);
;                 }
;             if (rare) {
;                 lrun *= fpost;
; #pragma unroll
;                 for (int db = 0; db < 2; ++db)
; #pragma unroll
;                     for (int r = 0; r < 16; ++r) oacc[db][r] *= fpost;
;             }
;         }
.Lat0_mid1:
	v_add_u32 v193, s8, v193
	v_add_u32 v200, s8, v200
	v_add_u32 v201, s8, v201
	s_barrier
	s_nop 7
	v_mfma_f32_32x32x16_bf16 v[16:31], v[146:149], v[48:51], v[16:31]
	ds_read_b64_tr_b16 v[170:171], v191 offset:6144
	ds_read_b64_tr_b16 v[172:173], v191 offset:7168
	v_max3_f32 v211, v211, v80, v81
	v_exp_f32 v80, v80
	v_exp_f32 v81, v81
	v_max3_f32 v211, v211, v82, v83
	v_exp_f32 v82, v82
	v_exp_f32 v83, v83
	v_add_f32 v188, v80, v81
	v_cvt_pk_bf16_f32 v80, v80, v81
	v_max3_f32 v211, v211, v84, v85
	v_exp_f32 v84, v84
	v_exp_f32 v85, v85
	v_add_f32 v188, v188, v82
	v_mfma_f32_32x32x16_bf16 v[32:47], v[150:153], v[48:51], v[32:47]
	ds_read_b64_tr_b16 v[174:175], v192 offset:6144
	ds_read_b64_tr_b16 v[176:177], v192 offset:7168
	v_add_f32 v188, v188, v83
	v_cvt_pk_bf16_f32 v81, v82, v83
	v_max3_f32 v211, v211, v86, v87
	v_exp_f32 v86, v86
	v_exp_f32 v87, v87
	v_add_f32 v188, v188, v84
	v_add_f32 v188, v188, v85
	v_cvt_pk_bf16_f32 v82, v84, v85
	v_max3_f32 v211, v211, v88, v89
	v_exp_f32 v88, v88
	v_exp_f32 v89, v89
	v_add_f32 v188, v188, v86
	v_mfma_f32_32x32x16_bf16 v[16:31], v[154:157], v[52:55], v[16:31]
	ds_read_b64_tr_b16 v[146:147], v191 offset:8192
	ds_read_b64_tr_b16 v[148:149], v191 offset:9216
	v_add_f32 v188, v188, v87
	v_cvt_pk_bf16_f32 v83, v86, v87
	v_max3_f32 v211, v211, v90, v91
	v_exp_f32 v90, v90
	v_exp_f32 v91, v91
	v_add_f32 v188, v188, v88
	v_add_f32 v188, v188, v89
	v_cvt_pk_bf16_f32 v84, v88, v89
	v_max3_f32 v211, v211, v92, v93
	v_exp_f32 v92, v92
	v_exp_f32 v93, v93
	v_add_f32 v188, v188, v90
	s_waitcnt lgkmcnt(10)
	v_mfma_f32_32x32x16_bf16 v[32:47], v[158:161], v[52:55], v[32:47]
	ds_read_b64_tr_b16 v[150:151], v192 offset:8192
	ds_read_b64_tr_b16 v[152:153], v192 offset:9216
	v_add_f32 v188, v188, v91
	v_cvt_pk_bf16_f32 v85, v90, v91
	v_max3_f32 v211, v211, v94, v95
	v_exp_f32 v94, v94
	v_exp_f32 v95, v95
	v_add_f32 v188, v188, v92
	v_add_f32 v188, v188, v93
	v_cvt_pk_bf16_f32 v86, v92, v93
	v_add_f32 v188, v188, v94
	v_add_f32 v188, v188, v95
	v_cvt_pk_bf16_f32 v87, v94, v95
	v_max3_f32 v211, v211, v96, v97
	s_waitcnt lgkmcnt(10)
	v_mfma_f32_32x32x16_bf16 v[16:31], v[162:165], v[64:67], v[16:31]
	ds_read_b64_tr_b16 v[154:155], v191 offset:10240
	ds_read_b64_tr_b16 v[156:157], v191 offset:11264
	v_exp_f32 v96, v96
	v_exp_f32 v97, v97
	v_max3_f32 v211, v211, v98, v99
	v_exp_f32 v98, v98
	v_exp_f32 v99, v99
	v_add_f32 v188, v188, v96
	v_add_f32 v188, v188, v97
	v_cvt_pk_bf16_f32 v96, v96, v97
	v_max3_f32 v211, v211, v100, v101
	v_exp_f32 v100, v100
	v_exp_f32 v101, v101
	v_add_f32 v188, v188, v98
	s_waitcnt lgkmcnt(10)
	v_mfma_f32_32x32x16_bf16 v[32:47], v[166:169], v[64:67], v[32:47]
	ds_read_b64_tr_b16 v[158:159], v192 offset:10240
	ds_read_b64_tr_b16 v[160:161], v192 offset:11264
	v_add_f32 v188, v188, v99
	v_cvt_pk_bf16_f32 v97, v98, v99
	v_max3_f32 v211, v211, v102, v103
	v_exp_f32 v102, v102
	v_exp_f32 v103, v103
	v_add_f32 v188, v188, v100
	v_add_f32 v188, v188, v101
	v_cvt_pk_bf16_f32 v98, v100, v101
	v_max3_f32 v211, v211, v104, v105
	v_exp_f32 v104, v104
	v_exp_f32 v105, v105
	v_add_f32 v188, v188, v102
	s_waitcnt lgkmcnt(10)
	v_mfma_f32_32x32x16_bf16 v[16:31], v[170:173], v[68:71], v[16:31]
	ds_read_b64_tr_b16 v[162:163], v191 offset:12288
	ds_read_b64_tr_b16 v[164:165], v191 offset:13312
	v_add_f32 v188, v188, v103
	v_cvt_pk_bf16_f32 v99, v102, v103
	v_max3_f32 v211, v211, v106, v107
	v_exp_f32 v106, v106
	v_exp_f32 v107, v107
	v_add_f32 v188, v188, v104
	v_add_f32 v188, v188, v105
	v_cvt_pk_bf16_f32 v100, v104, v105
	v_max3_f32 v211, v211, v108, v109
	v_exp_f32 v108, v108
	v_exp_f32 v109, v109
	v_add_f32 v188, v188, v106
	s_waitcnt lgkmcnt(10)
	v_mfma_f32_32x32x16_bf16 v[32:47], v[174:177], v[68:71], v[32:47]
	ds_read_b64_tr_b16 v[166:167], v192 offset:12288
	ds_read_b64_tr_b16 v[168:169], v192 offset:13312
	v_add_f32 v188, v188, v107
	v_cvt_pk_bf16_f32 v101, v106, v107
	v_max3_f32 v211, v211, v110, v111
	v_exp_f32 v110, v110
	v_exp_f32 v111, v111
	v_add_f32 v188, v188, v108
	v_add_f32 v188, v188, v109
	v_cvt_pk_bf16_f32 v102, v108, v109
	v_add_f32 v188, v188, v110
	v_add_f32 v188, v188, v111
	v_cvt_pk_bf16_f32 v103, v110, v111
	v_add_f32 v206, v206, v188
	s_waitcnt lgkmcnt(10)
	v_mfma_f32_32x32x16_bf16 v[16:31], v[146:149], v[80:83], v[16:31]
	ds_read_b64_tr_b16 v[170:171], v191 offset:14336
	ds_read_b64_tr_b16 v[172:173], v191 offset:15360
	s_waitcnt lgkmcnt(10)
	v_mfma_f32_32x32x16_bf16 v[32:47], v[150:153], v[80:83], v[32:47]
	ds_read_b64_tr_b16 v[174:175], v192 offset:14336
	ds_read_b64_tr_b16 v[176:177], v192 offset:15360
	v_add_u32 v191, s58, v191
	v_add_u32 v192, s58, v192
	s_waitcnt lgkmcnt(10)
	v_mfma_f32_32x32x16_bf16 v[16:31], v[154:157], v[84:87], v[16:31]
	ds_read_b128 v[146:149], v190 offset:0
	s_waitcnt lgkmcnt(9)
	v_mfma_f32_32x32x16_bf16 v[32:47], v[158:161], v[84:87], v[32:47]
	ds_read_b128 v[150:153], v190 offset:6656
	s_waitcnt lgkmcnt(8)
	v_mfma_f32_32x32x16_bf16 v[16:31], v[162:165], v[96:99], v[16:31]
	ds_read_b128 v[154:157], v190 offset:32
	s_waitcnt lgkmcnt(7)
	v_mfma_f32_32x32x16_bf16 v[32:47], v[166:169], v[96:99], v[32:47]
	ds_read_b128 v[158:161], v190 offset:6688
	s_waitcnt lgkmcnt(6)
	v_mfma_f32_32x32x16_bf16 v[16:31], v[170:173], v[100:103], v[16:31]
	ds_read_b128 v[162:165], v190 offset:64
	s_waitcnt lgkmcnt(5)
	v_mfma_f32_32x32x16_bf16 v[32:47], v[174:177], v[100:103], v[32:47]
	ds_read_b128 v[166:169], v190 offset:6720
	v_cmp_gt_f32_e64 s[40:41], v211, v207
	s_cmp_lg_u64 s[40:41], 0
	s_cbranch_scc0 .Lat0_pairend2
	v_mov_b32 v1, v211
	s_nop 1
	v_permlane32_swap_b32 v1, v211
	v_max_f32 v1, v1, v211
	v_cmp_gt_f32 vcc, v1, v207
	s_nop 1
	v_cndmask_b32 v14, v205, v1, vcc
	v_sub_f32 v15, v205, v14
	v_exp_f32 v15, v15
	v_mov_b32 v205, v14
	v_add_f32 v207, 0x41000000, v14
	v_mul_f32 v16, v16, v15
	v_mul_f32 v17, v17, v15
	v_mul_f32 v18, v18, v15
	v_mul_f32 v19, v19, v15
	v_mul_f32 v20, v20, v15
	v_mul_f32 v21, v21, v15
	v_mul_f32 v22, v22, v15
	v_mul_f32 v23, v23, v15
	v_mul_f32 v24, v24, v15
	v_mul_f32 v25, v25, v15
	v_mul_f32 v26, v26, v15
	v_mul_f32 v27, v27, v15
	v_mul_f32 v28, v28, v15
	v_mul_f32 v29, v29, v15
	v_mul_f32 v30, v30, v15
	v_mul_f32 v31, v31, v15
	v_mul_f32 v32, v32, v15
	v_mul_f32 v33, v33, v15
	v_mul_f32 v34, v34, v15
	v_mul_f32 v35, v35, v15
	v_mul_f32 v36, v36, v15
	v_mul_f32 v37, v37, v15
	v_mul_f32 v38, v38, v15
	v_mul_f32 v39, v39, v15
	v_mul_f32 v40, v40, v15
	v_mul_f32 v41, v41, v15
	v_mul_f32 v42, v42, v15
	v_mul_f32 v43, v43, v15
	v_mul_f32 v44, v44, v15
	v_mul_f32 v45, v45, v15
	v_mul_f32 v46, v46, v15
	v_mul_f32 v47, v47, v15
	v_mul_f32 v206, v206, v15
	v_cmp_neq_f32_e64 s[36:37], 0, v205
	s_branch .Lat0_pairend2
.Lat0_gen:
	s_waitcnt lgkmcnt(0)
	s_lshl_b32 s58, s26, 1
	s_lshl_b32 s8, s47, 2
	s_sub_u32 s58, s58, s8

; #define LAS __attribute__((address_space(3)))
; __device__ __forceinline__ unsigned cvt_pk(float lo, float hi) { f32x2_t v = {lo, hi}; bf16x2_t b = __builtin_convertvector(v, bf16x2_t); return __builtin_bit_cast(unsigned, b); }
; __device__ __forceinline__ int fresh_tid() { int t; asm volatile("v_mov_b32 %0, %1" : "=v"(t) : "v"(threadIdx.x)); return t; }
; template <int TYPE>
; __device__ __forceinline__ void attn_item(const Ctx& a, int b, int h, int qt, LAS unsigned char* lds) {
;     constexpr int DK = TYPE == 0 ? 96 : 64, KLD = DK + 8, KBYTES = 128 * KLD * 2, VLD = 132, VBYTES = 64 * VLD * 2, BUF = KBYTES + VBYTES, NKK = DK / 16;
;     constexpr int NKC = TYPE == 0 ? 3 : 2;
;     const int tid = fresh_tid(), lane = tid & 63, wv = tid >> 6, l32 = lane & 31, hb = lane >> 5;
;     const bf16_t* mr = (const bf16_t*)(a.ws + B_MLA); const bf16_t* pa = (const bf16_t*)(a.ws + B_PROJ); const bf16_t* kro = (const bf16_t*)(a.ws + B_KROPE);
;     bf16_t* br = (bf16_t*)(a.ws + B_BRANCH);
;     const int qrow = qt * 256 + wv * 32 + l32;
;     bf16x8 Q[NKK];
;     {
;         const bf16_t* qp = TYPE == 0 ? mr + (size_t)qrow * MR + h * 96 : pa + (size_t)qrow * PA + C_MQ + h * 64;
; #pragma unroll
;         for (int kk = 0; kk < NKK; ++kk) Q[kk] = *(const bf16x8*)(qp + kk * 16 + hb * 8);
;     }
;     unsigned qmask = 0xffffffffu;
;     if (TYPE == 1) qmask = ((const unsigned*)(a.ws + WS_MASK))[(size_t)h * SEQ + qrow];
;     f32x16 oacc[2];
; #pragma unroll
;     for (int db = 0; db < 2; ++db)
; #pragma unroll
;         for (int r = 0; r < 16; ++r) oacc[db][r] = 0.f;
;     float mrun = 0.f, lrun = 0.f;
;     const int npair = (qt + 1) * 2;
;     u32x4 kreg[NKC], vreg[2];
;     ...
;     AT_LOAD(0); AT_STORE(0);
;     __syncthreads();
;     ...
;     lrun += __shfl_xor(lrun, 32);
;     const float inv = 1.f / lrun;
;     bf16_t* op = br + ((size_t)b * SEQ + qrow) * BR + (TYPE == 0 ? 0 : 1024) + h * 64;
; #pragma unroll
;     for (int db = 0; db < 2; ++db)
; #pragma unroll
;         for (int g = 0; g < 4; ++g) {
;             u32x2 w; w[0] = cvt_pk(oacc[db][g * 4 + 0] * inv, oacc[db][g * 4 + 1] * inv); w[1] = cvt_pk(oacc[db][g * 4 + 2] * inv, oacc[db][g * 4 + 3] * inv);
;             *(u32x2*)(op + db * 32 + g * 8 + hb * 4) = w;
;         }
.Lat0_g1_end:
.Lat0_pairend:
	s_cmp_eq_u32 s12, 2
	s_cselect_b32 s8, 0x1f800, 0
	s_sub_u32 s8, 0xa800, s8
	v_add_u32 v190, s8, v190
	v_add_u32 v191, s8, v191
	v_add_u32 v192, s8, v192
	s_add_u32 s12, s12, 1
	s_cmp_eq_u32 s12, 3
	s_cselect_b32 s12, 0, s12
	ds_read_b128 v[146:149], v190 offset:0
	ds_read_b128 v[150:153], v190 offset:6656
	ds_read_b128 v[154:157], v190 offset:32
	ds_read_b128 v[158:161], v190 offset:6688
	ds_read_b128 v[162:165], v190 offset:64
	ds_read_b128 v[166:169], v190 offset:6720
.Lat0_pairend2:
	s_add_u32 s26, s26, 1
	s_cmp_lt_u32 s26, s30
	s_cbranch_scc1 .Lat0_loop
.Lat0_epi:
	s_waitcnt lgkmcnt(0)
	v_mov_b32 v1, v206
	s_nop 1
	v_permlane32_swap_b32 v1, v206
	v_add_f32 v1, v1, v206
	v_div_scale_f32 v4, s[0:1], v1, v1, 1.0
	v_rcp_f32 v5, v4
	v_div_scale_f32 v6, vcc, 1.0, v1, 1.0
	v_fma_f32 v7, -v4, v5, 1.0
	v_fmac_f32 v5, v7, v5
	v_mul_f32 v7, v6, v5
	v_fma_f32 v8, -v4, v7, v6
	v_fmac_f32 v7, v8, v5
	v_fma_f32 v4, -v4, v7, v6
	v_div_fmas_f32 v4, v4, v5, v7
	v_div_fixup_f32 v4, v4, v1, 1.0
	v_readlane_b32 s8, v255, 7
	s_mul_i32 s8, s8, 0xc00
	s_lshl_b32 s9, s50, 7
	s_add_u32 s8, s8, s9
	s_add_u32 s56, s18, s8
	s_addc_u32 s57, s19, 0
	s_movk_i32 s8, 0xc00
	v_mul_lo_u32 v181, v144, s8
	v_lshrrev_b32 v15, 5, v195
	v_lshl_add_u32 v181, v15, 3, v181
	v_mul_f32 v6, v4, v16
	v_mul_f32 v7, v4, v17
	v_mul_f32 v8, v4, v18
	v_mul_f32 v9, v4, v19
	v_cvt_pk_bf16_f32 v10, v6, v7
	v_cvt_pk_bf16_f32 v11, v8, v9
	global_store_dwordx2 v181, v[10:11], s[56:57] offset:0
	v_mul_f32 v6, v4, v20
	v_mul_f32 v7, v4, v21
	v_mul_f32 v8, v4, v22
	v_mul_f32 v9, v4, v23
	v_cvt_pk_bf16_f32 v12, v6, v7
	v_cvt_pk_bf16_f32 v13, v8, v9
	global_store_dwordx2 v181, v[12:13], s[56:57] offset:16
	v_mul_f32 v6, v4, v24
	v_mul_f32 v7, v4, v25
	v_mul_f32 v8, v4, v26
	v_mul_f32 v9, v4, v27
	v_cvt_pk_bf16_f32 v10, v6, v7
	v_cvt_pk_bf16_f32 v11, v8, v9
	global_store_dwordx2 v181, v[10:11], s[56:57] offset:32
	v_mul_f32 v6, v4, v28
	v_mul_f32 v7, v4, v29
	v_mul_f32 v8, v4, v30
	v_mul_f32 v9, v4, v31
	v_cvt_pk_bf16_f32 v12, v6, v7
	v_cvt_pk_bf16_f32 v13, v8, v9
	global_store_dwordx2 v181, v[12:13], s[56:57] offset:48
	v_mul_f32 v6, v4, v32
	v_mul_f32 v7, v4, v33
	v_mul_f32 v8, v4, v34
	v_mul_f32 v9, v4, v35
	v_cvt_pk_bf16_f32 v10, v6, v7
	v_cvt_pk_bf16_f32 v11, v8, v9
	global_store_dwordx2 v181, v[10:11], s[56:57] offset:64
	v_mul_f32 v6, v4, v36
	v_mul_f32 v7, v4, v37
	v_mul_f32 v8, v4, v38
	v_mul_f32 v9, v4, v39
	v_cvt_pk_bf16_f32 v12, v6, v7
	v_cvt_pk_bf16_f32 v13, v8, v9
	global_store_dwordx2 v181, v[12:13], s[56:57] offset:80
	v_mul_f32 v6, v4, v40
	v_mul_f32 v7, v4, v41
	v_mul_f32 v8, v4, v42
	v_mul_f32 v9, v4, v43
	v_cvt_pk_bf16_f32 v10, v6, v7
	v_cvt_pk_bf16_f32 v11, v8, v9
	global_store_dwordx2 v181, v[10:11], s[56:57] offset:96
	v_mul_f32 v6, v4, v44
	v_mul_f32 v7, v4, v45
	v_mul_f32 v8, v4, v46
	v_mul_f32 v9, v4, v47
	v_cvt_pk_bf16_f32 v12, v6, v7
	v_cvt_pk_bf16_f32 v13, v8, v9
	global_store_dwordx2 v181, v[12:13], s[56:57] offset:112
	s_barrier
	s_mov_b64 s[0:1], -1
	s_branch .LBB0_296
.Lat1_entry:
	s_lshr_b32 s47, s12, 4
	s_sub_u32 s47, 31, s47
	s_and_b32 s50, s12, 7
	v_lshrrev_b32 v1, 6, v179
	s_add_u32 s30, s47, 1
	s_lshl_b32 s30, s30, 1
	v_readfirstlane_b32 s51, v1
	v_and_b32 v14, 31, v195
	v_lshrrev_b32 v15, 5, v195
	s_lshl_b32 s8, s47, 8
	s_lshl_b32 s9, s51, 5
	s_add_u32 s8, s8, s9
	v_add_u32 v144, s8, v14
	v_add_u32 v208, s9, v14
	v_lshlrev_b32 v181, 2, v15
	v_sub_u32 v208, v208, v181
	s_lshl_b32 s9, s50, 7
	s_add_u32 s56, s70, 0x1350
	s_addc_u32 s57, s71, 0
	s_add_u32 s56, s56, s9
	s_addc_u32 s57, s57, 0
	v_lshlrev_b32 v181, 13, v144
	v_lshl_add_u32 v181, v15, 4, v181
	global_load_dwordx4 v[112:115], v181, s[56:57] offset:0
	global_load_dwordx4 v[116:119], v181, s[56:57] offset:32
	global_load_dwordx4 v[120:123], v181, s[56:57] offset:64
	global_load_dwordx4 v[124:127], v181, s[56:57] offset:96
	s_lshl_b32 s9, s50, 15
	s_add_u32 s56, s16, 0x58b0000
	s_addc_u32 s57, s17, 0
	s_add_u32 s56, s56, s9
	s_addc_u32 s57, s57, 0
	v_lshlrev_b32 v212, 2, v144
	global_load_dword v209, v212, s[56:57]
	v_lshrrev_b32 v181, 3, v179
	v_and_b32 v212, 7, v179
	s_lshl_b32 s9, s50, 7
	s_add_u32 s52, s70, 0x1750
	s_addc_u32 s53, s71, 0
	s_add_u32 s52, s52, s9
	s_addc_u32 s53, s53, 0
	v_lshlrev_b32 v184, 13, v181
	v_lshl_add_u32 v184, v212, 4, v184
	v_add_u32 v185, 0x80000, v184
	v_mul_u32_u24 v190, 144, v14
	v_lshl_add_u32 v190, v15, 4, v190
	v_mul_u32_u24 v193, 144, v181
	v_lshl_add_u32 v193, v212, 4, v193
	v_and_b32 v1, 2, v181
	v_lshlrev_b32 v1, 5, v1
	v_lshlrev_b32 v188, 4, v212
	v_xor_b32 v1, v1, v188
	v_lshl_add_u32 v200, v181, 7, v1
	v_add_u32 v200, 18432, v200
	v_bfe_u32 v1, v195, 2, 2
	v_lshlrev_b32 v191, 7, v1
	v_bfe_u32 v1, v195, 3, 1
	v_lshl_add_u32 v191, v1, 6, v191
	v_bfe_u32 v1, v195, 4, 1
	v_lshl_add_u32 v191, v1, 5, v191
	v_and_b32 v1, 3, v195
	v_lshl_add_u32 v191, v1, 3, v191
	v_lshl_add_u32 v191, v15, 9, v191
	v_add_u32 v191, 18432, v191
	v_xor_b32 v192, 64, v191
	global_load_dwordx4 v[2:5], v184, s[52:53]
	global_load_dwordx4 v[6:9], v184, s[52:53] offset:1024
	global_load_dwordx4 v[10:13], v185, s[52:53]
	global_load_dwordx4 v[136:139], v185, s[52:53] offset:1024
	s_add_u32 s52, s52, 0x100000
	s_addc_u32 s53, s53, 0
	v_mov_b32 v16, 0
	v_mov_b32 v17, 0
	v_mov_b32 v18, 0
	v_mov_b32 v19, 0
	v_mov_b32 v20, 0
	v_mov_b32 v21, 0
	v_mov_b32 v22, 0
	v_mov_b32 v23, 0
	v_mov_b32 v24, 0
	v_mov_b32 v25, 0
	v_mov_b32 v26, 0
	v_mov_b32 v27, 0
	v_mov_b32 v28, 0
	v_mov_b32 v29, 0
	v_mov_b32 v30, 0
	v_mov_b32 v31, 0
	v_mov_b32 v32, 0
	v_mov_b32 v33, 0
	v_mov_b32 v34, 0
	v_mov_b32 v35, 0
	v_mov_b32 v36, 0
	v_mov_b32 v37, 0
	v_mov_b32 v38, 0
	v_mov_b32 v39, 0
	v_mov_b32 v40, 0
	v_mov_b32 v41, 0
	v_mov_b32 v42, 0
	v_mov_b32 v43, 0
	v_mov_b32 v44, 0
	v_mov_b32 v45, 0
	v_mov_b32 v46, 0
	v_mov_b32 v47, 0
	v_mov_b32 v205, 0
	v_mov_b32 v206, 0
	v_mov_b32 v207, 0x41000000
	s_mov_b64 s[36:37], 0
	s_mov_b32 s26, 0
	s_waitcnt vmcnt(0)
	ds_write_b128 v193, v[2:5]
	ds_write_b128 v193, v[10:13] offset:9216
	ds_write_b128 v200, v[6:9]
	ds_write_b128 v200, v[136:139] offset:8192
	s_waitcnt lgkmcnt(0)
	global_load_dwordx4 v[2:5], v184, s[52:53]
	global_load_dwordx4 v[6:9], v184, s[52:53] offset:1024
	global_load_dwordx4 v[10:13], v185, s[52:53]
	global_load_dwordx4 v[136:139], v185, s[52:53] offset:1024
	s_add_u32 s52, s52, 0x100000
	s_addc_u32 s53, s53, 0
	s_mov_b32 s8, 0x8800
	v_add_u32 v193, s8, v193
	v_add_u32 v200, s8, v200
	s_mov_b32 s12, 0
	s_mov_b32 s13, 1
	s_waitcnt lgkmcnt(0)
	s_barrier
	ds_read_b128 v[146:149], v190 offset:0
	ds_read_b128 v[150:153], v190 offset:4608
	ds_read_b128 v[154:157], v190 offset:32
	ds_read_b128 v[158:161], v190 offset:4640
	ds_read_b128 v[162:165], v190 offset:64
	ds_read_b128 v[166:169], v190 offset:4672
; template <int TYPE>
; __device__ __forceinline__ void attn_item(const Ctx& a, int b, int h, int qt, LAS unsigned char* lds) {
;     ...
; #pragma unroll
;         for (int kk = 0; kk < NKK; ++kk)
; #pragma unroll
;             for (int sub = 0; sub < 2; ++sub)
;                 if (act[sub]) {
; #pragma unroll
;                     for (int kb = 0; kb < 2; ++kb) {
;                         bf16x8 ka = *(const LAS bf16x8*)(Kt + (sub * 64 + kb * 32 + l32) * KLD + kk * 16 + hb * 8);
;                         s[sub][kb] = __builtin_amdgcn_mfma_f32_32x32x16_bf16(ka, Q[kk], s[sub][kb], 0, 0, 0);
;                     }
;                 }
; #pragma unroll
;         for (int sub = 0; sub < 2; ++sub) {
;             if (!act[sub]) continue;
;             const int kt = kp * 2 + sub, kloc = kt - qt * 4;
;             if (kloc >= 0) {
; #pragma unroll
;                 for (int kb = 0; kb < 2; ++kb)
; #pragma unroll
;                     for (int r = 0; r < 16; ++r) { int kabs = kt * 64 + kb * 32 + (r >> 2) * 8 + hb * 4 + (r & 3); if (kabs > qrow) s[sub][kb][r] = -1e30f; }
;             } else if (TYPE == 1) {
;                 if (!((qmask >> (kt >> 2)) & 1u)) {
; #pragma unroll
;                     for (int kb = 0; kb < 2; ++kb)
; #pragma unroll
;                         for (int r = 0; r < 16; ++r) s[sub][kb][r] = -1e30f;
;                 }
;             }
;             float mx = -1e30f;
; #pragma unroll
;             for (int kb = 0; kb < 2; ++kb)
; #pragma unroll
;                 for (int r = 0; r < 16; ++r) mx = fmaxf(mx, s[sub][kb][r]);
;             mx = fmaxf(mx, __shfl_xor(mx, 32));
;             const float delta = mrun - mref;
;             const bool bump = (mx - delta) > 8.f;
;             const bool rare = __builtin_amdgcn_ballot_w64(bump || delta != 0.f) != 0ull;
;             float fpost = 1.f;
;             if (rare) {
;                 const float mnew = bump ? mref + mx : mrun;
;                 const float pre = __builtin_amdgcn_exp2f(delta);
;                 fpost = __builtin_amdgcn_exp2f(mref - mnew);
;                 mrun = mnew;
;                 lrun *= pre;
; #pragma unroll
;                 for (int db = 0; db < 2; ++db)
; #pragma unroll
;                     for (int r = 0; r < 16; ++r) oacc[db][r] *= pre;
;             }
;             float ps = 0.f;
; #pragma unroll
;             for (int kb = 0; kb < 2; ++kb)
; #pragma unroll
.Lat1_loop:
	s_add_u32 s8, s26, 2
	s_cmp_ge_u32 s8, s30
	s_cselect_b32 s57, 1, 0
	s_lshr_b32 s8, s26, 1
	v_lshrrev_b32 v1, s8, v209
	v_and_b32 v1, 1, v1
	v_sub_u32 v210, 0, v1
	v_cmp_ne_u32_e64 s[38:39], 0, v1
	s_cmp_eq_u32 s57, 1
	s_cbranch_scc1 .Lat1_gen
	s_cmp_eq_u64 s[38:39], 0
	s_cbranch_scc1 .Lat1_skip
	s_cmp_lg_u64 s[36:37], 0
	s_cbranch_scc1 .Lat1_gen
	v_mov_b32 v211, v0
	s_cmp_eq_u32 s12, 2
	s_cselect_b32 s58, 0x19800, 0
	s_sub_u32 s58, 0x8800, s58
	s_add_u32 s12, s12, 1
	s_cmp_eq_u32 s12, 3
	s_cselect_b32 s12, 0, s12
	s_waitcnt lgkmcnt(5)
	v_mfma_f32_32x32x16_bf16 v[48:63], v[146:149], v[112:115], 0
	ds_read_b128 v[170:173], v190 offset:96
	s_waitcnt lgkmcnt(5)
	v_mfma_f32_32x32x16_bf16 v[64:79], v[150:153], v[112:115], 0
	ds_read_b128 v[174:177], v190 offset:4704
	s_waitcnt lgkmcnt(5)
	v_mfma_f32_32x32x16_bf16 v[48:63], v[154:157], v[116:119], v[48:63]
	ds_read_b128 v[146:149], v190 offset:9216
	s_waitcnt lgkmcnt(5)
	v_mfma_f32_32x32x16_bf16 v[64:79], v[158:161], v[116:119], v[64:79]
	ds_read_b128 v[150:153], v190 offset:13824
	s_waitcnt lgkmcnt(5)
	v_mfma_f32_32x32x16_bf16 v[48:63], v[162:165], v[120:123], v[48:63]
	ds_read_b128 v[154:157], v190 offset:9248
	s_waitcnt lgkmcnt(5)
	v_mfma_f32_32x32x16_bf16 v[64:79], v[166:169], v[120:123], v[64:79]
	ds_read_b128 v[158:161], v190 offset:13856
	s_waitcnt lgkmcnt(5)
	v_mfma_f32_32x32x16_bf16 v[48:63], v[170:173], v[124:127], v[48:63]
	ds_read_b128 v[162:165], v190 offset:9280
	s_waitcnt lgkmcnt(5)
	v_mfma_f32_32x32x16_bf16 v[64:79], v[174:177], v[124:127], v[64:79]
	ds_read_b128 v[166:169], v190 offset:13888
	s_waitcnt vmcnt(0)
	s_waitcnt lgkmcnt(5)
	v_mfma_f32_32x32x16_bf16 v[80:95], v[146:149], v[112:115], 0
	ds_read_b128 v[170:173], v190 offset:9312
	s_nop 3
	v_max3_f32 v211, v211, v48, v49
	v_exp_f32 v48, v48
	v_exp_f32 v49, v49
	v_max3_f32 v211, v211, v50, v51
	v_exp_f32 v50, v50
	v_exp_f32 v51, v51
	v_add_f32 v188, v48, v49
	v_cvt_pk_bf16_f32 v48, v48, v49
	v_and_b32 v48, v48, v210
	v_max3_f32 v211, v211, v52, v53
	v_exp_f32 v52, v52
	v_exp_f32 v53, v53
	v_add_f32 v188, v188, v50
	v_add_f32 v188, v188, v51
	s_waitcnt lgkmcnt(5)
	v_mfma_f32_32x32x16_bf16 v[96:111], v[150:153], v[112:115], 0
	ds_write_b128 v193, v[2:5]
	ds_read_b128 v[174:177], v190 offset:13920
	v_add_u32 v190, s58, v190
	v_cvt_pk_bf16_f32 v49, v50, v51
	v_and_b32 v49, v49, v210
	v_max3_f32 v211, v211, v54, v55
	v_exp_f32 v54, v54
	v_exp_f32 v55, v55
	v_add_f32 v188, v188, v52
	v_add_f32 v188, v188, v53
	v_cvt_pk_bf16_f32 v50, v52, v53
	v_and_b32 v50, v50, v210
	v_max3_f32 v211, v211, v56, v57
	v_exp_f32 v56, v56
	v_exp_f32 v57, v57
	v_add_f32 v188, v188, v54
	v_add_f32 v188, v188, v55
	s_waitcnt lgkmcnt(6)
	v_mfma_f32_32x32x16_bf16 v[80:95], v[154:157], v[116:119], v[80:95]
	ds_read_b64_tr_b16 v[146:147], v191 offset:0
	ds_read_b64_tr_b16 v[148:149], v191 offset:1024
	v_cvt_pk_bf16_f32 v51, v54, v55
	v_and_b32 v51, v51, v210
	v_max3_f32 v211, v211, v58, v59
	v_exp_f32 v58, v58
	v_exp_f32 v59, v59
	v_add_f32 v188, v188, v56
	v_add_f32 v188, v188, v57
	v_cvt_pk_bf16_f32 v52, v56, v57
	v_and_b32 v52, v52, v210
	v_max3_f32 v211, v211, v60, v61
	v_exp_f32 v60, v60
	v_exp_f32 v61, v61
	v_add_f32 v188, v188, v58
	v_add_f32 v188, v188, v59
	s_waitcnt lgkmcnt(7)
	v_mfma_f32_32x32x16_bf16 v[96:111], v[158:161], v[116:119], v[96:111]
	ds_write_b128 v193, v[10:13] offset:9216
	ds_read_b64_tr_b16 v[150:151], v192 offset:0
	ds_read_b64_tr_b16 v[152:153], v192 offset:1024
	v_cvt_pk_bf16_f32 v53, v58, v59
	v_and_b32 v53, v53, v210
	v_max3_f32 v211, v211, v62, v63
	v_exp_f32 v62, v62
	v_exp_f32 v63, v63
	v_add_f32 v188, v188, v60
	v_add_f32 v188, v188, v61
	v_cvt_pk_bf16_f32 v54, v60, v61
	v_and_b32 v54, v54, v210
	v_add_f32 v188, v188, v62
	v_add_f32 v188, v188, v63
	v_cvt_pk_bf16_f32 v55, v62, v63
	v_and_b32 v55, v55, v210
	v_max3_f32 v211, v211, v64, v65
	s_waitcnt lgkmcnt(9)
	v_mfma_f32_32x32x16_bf16 v[80:95], v[162:165], v[120:123], v[80:95]
	ds_read_b64_tr_b16 v[154:155], v191 offset:2048
	ds_read_b64_tr_b16 v[156:157], v191 offset:3072
	v_exp_f32 v64, v64
	v_exp_f32 v65, v65
	v_max3_f32 v211, v211, v66, v67
	v_exp_f32 v66, v66
	v_exp_f32 v67, v67
	v_add_f32 v188, v188, v64
	v_add_f32 v188, v188, v65
	v_cvt_pk_bf16_f32 v64, v64, v65
	v_and_b32 v64, v64, v210
	v_max3_f32 v211, v211, v68, v69
	v_exp_f32 v68, v68
	v_exp_f32 v69, v69
	v_add_f32 v188, v188, v66
	v_add_f32 v188, v188, v67
	s_waitcnt lgkmcnt(10)
	v_mfma_f32_32x32x16_bf16 v[96:111], v[166:169], v[120:123], v[96:111]
	ds_write_b128 v200, v[6:9]
	ds_read_b64_tr_b16 v[158:159], v192 offset:2048
	ds_read_b64_tr_b16 v[160:161], v192 offset:3072
	v_cvt_pk_bf16_f32 v65, v66, v67
	v_and_b32 v65, v65, v210
	v_max3_f32 v211, v211, v70, v71
	v_exp_f32 v70, v70
	v_exp_f32 v71, v71
	v_add_f32 v188, v188, v68
	v_add_f32 v188, v188, v69
	v_cvt_pk_bf16_f32 v66, v68, v69
	v_and_b32 v66, v66, v210
	v_max3_f32 v211, v211, v72, v73
	v_exp_f32 v72, v72
	v_exp_f32 v73, v73
	v_add_f32 v188, v188, v70
	v_add_f32 v188, v188, v71
	s_waitcnt lgkmcnt(12)
	v_mfma_f32_32x32x16_bf16 v[80:95], v[170:173], v[124:127], v[80:95]
	ds_read_b64_tr_b16 v[162:163], v191 offset:4096
	ds_read_b64_tr_b16 v[164:165], v191 offset:5120
	v_cvt_pk_bf16_f32 v67, v70, v71
	v_and_b32 v67, v67, v210
	v_max3_f32 v211, v211, v74, v75
	v_exp_f32 v74, v74
	v_exp_f32 v75, v75
	v_add_f32 v188, v188, v72
	v_add_f32 v188, v188, v73
	v_cvt_pk_bf16_f32 v68, v72, v73
	v_and_b32 v68, v68, v210
	v_max3_f32 v211, v211, v76, v77
	v_exp_f32 v76, v76
	v_exp_f32 v77, v77
	v_add_f32 v188, v188, v74
	v_add_f32 v188, v188, v75
	s_waitcnt lgkmcnt(12)
	v_mfma_f32_32x32x16_bf16 v[96:111], v[174:177], v[124:127], v[96:111]
	ds_write_b128 v200, v[136:139] offset:8192
	ds_read_b64_tr_b16 v[166:167], v192 offset:4096
	ds_read_b64_tr_b16 v[168:169], v192 offset:5120
	v_cvt_pk_bf16_f32 v69, v74, v75
	v_and_b32 v69, v69, v210
	v_max3_f32 v211, v211, v78, v79
	v_exp_f32 v78, v78
	v_exp_f32 v79, v79
	v_add_f32 v188, v188, v76
	v_add_f32 v188, v188, v77
	v_cvt_pk_bf16_f32 v70, v76, v77
	v_and_b32 v70, v70, v210
	v_add_f32 v188, v188, v78
	v_add_f32 v188, v188, v79
	v_cvt_pk_bf16_f32 v71, v78, v79
	v_and_b32 v71, v71, v210
	v_and_b32 v188, v188, v210
	v_add_f32 v206, v206, v188
	s_cmp_eq_u32 s13, 2
	s_cselect_b32 s8, 0x19800, 0
	s_sub_u32 s8, 0x8800, s8
	s_add_u32 s13, s13, 1
	s_cmp_eq_u32 s13, 3
	s_cselect_b32 s13, 0, s13
	s_waitcnt lgkmcnt(2)
	s_add_u32 s9, s26, 2
	s_cmp_lt_u32 s9, s30
	s_cbranch_scc0 .Lat1_mid3
	global_load_dwordx4 v[2:5], v184, s[52:53]
	global_load_dwordx4 v[6:9], v184, s[52:53] offset:1024
	global_load_dwordx4 v[10:13], v185, s[52:53]
	global_load_dwordx4 v[136:139], v185, s[52:53] offset:1024
	s_add_u32 s52, s52, 0x100000
	s_addc_u32 s53, s53, 0
; template <int TYPE>
; __device__ __forceinline__ void attn_item(const Ctx& a, int b, int h, int qt, LAS unsigned char* lds) {
;     ...
;             float mx = -1e30f;
; #pragma unroll
;             for (int kb = 0; kb < 2; ++kb)
; #pragma unroll
;                 for (int r = 0; r < 16; ++r) mx = fmaxf(mx, s[sub][kb][r]);
;             mx = fmaxf(mx, __shfl_xor(mx, 32));
;             const float delta = mrun - mref;
;             const bool bump = (mx - delta) > 8.f;
;             const bool rare = __builtin_amdgcn_ballot_w64(bump || delta != 0.f) != 0ull;
;             float fpost = 1.f;
;             if (rare) {
;                 const float mnew = bump ? mref + mx : mrun;
;                 const float pre = __builtin_amdgcn_exp2f(delta);
;                 fpost = __builtin_amdgcn_exp2f(mref - mnew);
;                 mrun = mnew;
;                 lrun *= pre;
; #pragma unroll
;                 for (int db = 0; db < 2; ++db)
; #pragma unroll
;                     for (int r = 0; r < 16; ++r) oacc[db][r] *= pre;
;             }
;             float ps = 0.f;
; #pragma unroll
;             for (int kb = 0; kb < 2; ++kb)
; #pragma unroll
;                 for (int r = 0; r < 16; ++r) { float p = __builtin_amdgcn_exp2f(s[sub][kb][r]); s[sub][kb][r] = p; ps += p; }
;             lrun += ps;
; #pragma unroll
;             for (int kb = 0; kb < 2; ++kb)
; #pragma unroll
;                 for (int c = 0; c < 2; ++c) {
;                     bf16x8 pb = pack8(s[sub][kb], c);
; #pragma unroll
;                     for (int db = 0; db < 2; ++db)
;                         oacc[db] = __builtin_amdgcn_mfma_f32_32x32x16_bf16(lds_a2(VT + (db * 32 + l32) * VLD + sub * 64 + kb * 32 + c * 16 + hb * 4), pb, oacc[db], 0, 0, 0);
;                 }
;             if (rare) {
;                 lrun *= fpost;
; #pragma unroll
;                 for (int db = 0; db < 2; ++db)
; #pragma unroll
;                     for (int r = 0; r < 16; ++r) oacc[db][r] *= fpost;
;             }
;         }
.Lat1_mid3:
	v_add_u32 v193, s8, v193
	v_add_u32 v200, s8, v200
	s_barrier
	s_nop 7
	s_nop 0
	v_mfma_f32_32x32x16_bf16 v[16:31], v[146:149], v[48:51], v[16:31]
	ds_read_b64_tr_b16 v[170:171], v191 offset:6144
	ds_read_b64_tr_b16 v[172:173], v191 offset:7168
	v_max3_f32 v211, v211, v80, v81
	v_exp_f32 v80, v80
	v_exp_f32 v81, v81
	v_max3_f32 v211, v211, v82, v83
	v_exp_f32 v82, v82
	v_exp_f32 v83, v83
	v_add_f32 v188, v80, v81
	v_cvt_pk_bf16_f32 v80, v80, v81
	v_and_b32 v80, v80, v210
	v_max3_f32 v211, v211, v84, v85
	v_exp_f32 v84, v84
	v_exp_f32 v85, v85
	v_add_f32 v188, v188, v82
	v_add_f32 v188, v188, v83
	v_mfma_f32_32x32x16_bf16 v[32:47], v[150:153], v[48:51], v[32:47]
	ds_read_b64_tr_b16 v[174:175], v192 offset:6144
	ds_read_b64_tr_b16 v[176:177], v192 offset:7168
	v_cvt_pk_bf16_f32 v81, v82, v83
	v_and_b32 v81, v81, v210
	v_max3_f32 v211, v211, v86, v87
	v_exp_f32 v86, v86
	v_exp_f32 v87, v87
	v_add_f32 v188, v188, v84
	v_add_f32 v188, v188, v85
	v_cvt_pk_bf16_f32 v82, v84, v85
	v_and_b32 v82, v82, v210
	v_max3_f32 v211, v211, v88, v89
	v_exp_f32 v88, v88
	v_exp_f32 v89, v89
	v_add_f32 v188, v188, v86
	v_add_f32 v188, v188, v87
	v_mfma_f32_32x32x16_bf16 v[16:31], v[154:157], v[52:55], v[16:31]
	ds_read_b64_tr_b16 v[146:147], v191 offset:8192
	ds_read_b64_tr_b16 v[148:149], v191 offset:9216
	v_cvt_pk_bf16_f32 v83, v86, v87
	v_and_b32 v83, v83, v210
	v_max3_f32 v211, v211, v90, v91
	v_exp_f32 v90, v90
	v_exp_f32 v91, v91
	v_add_f32 v188, v188, v88
	v_add_f32 v188, v188, v89
	v_cvt_pk_bf16_f32 v84, v88, v89
	v_and_b32 v84, v84, v210
	v_max3_f32 v211, v211, v92, v93
	v_exp_f32 v92, v92
	v_exp_f32 v93, v93
	v_add_f32 v188, v188, v90
	v_add_f32 v188, v188, v91
	v_mfma_f32_32x32x16_bf16 v[32:47], v[158:161], v[52:55], v[32:47]
	ds_read_b64_tr_b16 v[150:151], v192 offset:8192
	ds_read_b64_tr_b16 v[152:153], v192 offset:9216
	v_cvt_pk_bf16_f32 v85, v90, v91
	v_and_b32 v85, v85, v210
	v_max3_f32 v211, v211, v94, v95
	v_exp_f32 v94, v94
	v_exp_f32 v95, v95
	v_add_f32 v188, v188, v92
	v_add_f32 v188, v188, v93
	v_cvt_pk_bf16_f32 v86, v92, v93
	v_and_b32 v86, v86, v210
	v_add_f32 v188, v188, v94
	v_add_f32 v188, v188, v95
	v_cvt_pk_bf16_f32 v87, v94, v95
	v_and_b32 v87, v87, v210
	v_max3_f32 v211, v211, v96, v97
	v_mfma_f32_32x32x16_bf16 v[16:31], v[162:165], v[64:67], v[16:31]
	ds_read_b64_tr_b16 v[154:155], v191 offset:10240
	ds_read_b64_tr_b16 v[156:157], v191 offset:11264
	v_exp_f32 v96, v96
	v_exp_f32 v97, v97
	v_max3_f32 v211, v211, v98, v99
	v_exp_f32 v98, v98
	v_exp_f32 v99, v99
	v_add_f32 v188, v188, v96
	v_add_f32 v188, v188, v97
	v_cvt_pk_bf16_f32 v96, v96, v97
	v_and_b32 v96, v96, v210
	v_max3_f32 v211, v211, v100, v101
	v_exp_f32 v100, v100
	v_exp_f32 v101, v101
	v_add_f32 v188, v188, v98
	v_add_f32 v188, v188, v99
	s_waitcnt lgkmcnt(10)
	v_mfma_f32_32x32x16_bf16 v[32:47], v[166:169], v[64:67], v[32:47]
	ds_read_b64_tr_b16 v[158:159], v192 offset:10240
	ds_read_b64_tr_b16 v[160:161], v192 offset:11264
	v_cvt_pk_bf16_f32 v97, v98, v99
	v_and_b32 v97, v97, v210
	v_max3_f32 v211, v211, v102, v103
	v_exp_f32 v102, v102
	v_exp_f32 v103, v103
	v_add_f32 v188, v188, v100
	v_add_f32 v188, v188, v101
	v_cvt_pk_bf16_f32 v98, v100, v101
	v_and_b32 v98, v98, v210
	v_max3_f32 v211, v211, v104, v105
	v_exp_f32 v104, v104
	v_exp_f32 v105, v105
	v_add_f32 v188, v188, v102
	v_add_f32 v188, v188, v103
	s_waitcnt lgkmcnt(10)
	v_mfma_f32_32x32x16_bf16 v[16:31], v[170:173], v[68:71], v[16:31]
	ds_read_b64_tr_b16 v[162:163], v191 offset:12288
	ds_read_b64_tr_b16 v[164:165], v191 offset:13312
	v_cvt_pk_bf16_f32 v99, v102, v103
	v_and_b32 v99, v99, v210
	v_max3_f32 v211, v211, v106, v107
	v_exp_f32 v106, v106
	v_exp_f32 v107, v107
	v_add_f32 v188, v188, v104
	v_add_f32 v188, v188, v105
	v_cvt_pk_bf16_f32 v100, v104, v105
	v_and_b32 v100, v100, v210
	v_max3_f32 v211, v211, v108, v109
	v_exp_f32 v108, v108
	v_exp_f32 v109, v109
	v_add_f32 v188, v188, v106
	v_add_f32 v188, v188, v107
	s_waitcnt lgkmcnt(10)
	v_mfma_f32_32x32x16_bf16 v[32:47], v[174:177], v[68:71], v[32:47]
	ds_read_b64_tr_b16 v[166:167], v192 offset:12288
	ds_read_b64_tr_b16 v[168:169], v192 offset:13312
	v_cvt_pk_bf16_f32 v101, v106, v107
	v_and_b32 v101, v101, v210
	v_max3_f32 v211, v211, v110, v111
	v_exp_f32 v110, v110
	v_exp_f32 v111, v111
	v_add_f32 v188, v188, v108
	v_add_f32 v188, v188, v109
	v_cvt_pk_bf16_f32 v102, v108, v109
	v_and_b32 v102, v102, v210
	v_add_f32 v188, v188, v110
	v_add_f32 v188, v188, v111
	v_cvt_pk_bf16_f32 v103, v110, v111
	v_and_b32 v103, v103, v210
	v_and_b32 v188, v188, v210
	v_add_f32 v206, v206, v188
	s_waitcnt lgkmcnt(10)
	v_mfma_f32_32x32x16_bf16 v[16:31], v[146:149], v[80:83], v[16:31]
	ds_read_b64_tr_b16 v[170:171], v191 offset:14336
	ds_read_b64_tr_b16 v[172:173], v191 offset:15360
	s_waitcnt lgkmcnt(10)
	v_mfma_f32_32x32x16_bf16 v[32:47], v[150:153], v[80:83], v[32:47]
	ds_read_b64_tr_b16 v[174:175], v192 offset:14336
	ds_read_b64_tr_b16 v[176:177], v192 offset:15360
	v_add_u32 v191, s58, v191
	v_add_u32 v192, s58, v192
	s_waitcnt lgkmcnt(10)
	v_mfma_f32_32x32x16_bf16 v[16:31], v[154:157], v[84:87], v[16:31]
	ds_read_b128 v[146:149], v190 offset:0
	s_waitcnt lgkmcnt(9)
	v_mfma_f32_32x32x16_bf16 v[32:47], v[158:161], v[84:87], v[32:47]
	ds_read_b128 v[150:153], v190 offset:4608
	s_waitcnt lgkmcnt(8)
	v_mfma_f32_32x32x16_bf16 v[16:31], v[162:165], v[96:99], v[16:31]
	ds_read_b128 v[154:157], v190 offset:32
	s_waitcnt lgkmcnt(7)
	v_mfma_f32_32x32x16_bf16 v[32:47], v[166:169], v[96:99], v[32:47]
	ds_read_b128 v[158:161], v190 offset:4640
	s_waitcnt lgkmcnt(6)
	v_mfma_f32_32x32x16_bf16 v[16:31], v[170:173], v[100:103], v[16:31]
	ds_read_b128 v[162:165], v190 offset:64
	s_waitcnt lgkmcnt(5)
	v_mfma_f32_32x32x16_bf16 v[32:47], v[174:177], v[100:103], v[32:47]
	ds_read_b128 v[166:169], v190 offset:4672
	v_cndmask_b32_e64 v211, v0, v211, s[38:39]
	v_cmp_gt_f32_e64 s[40:41], v211, v207
	s_cmp_lg_u64 s[40:41], 0
	s_cbranch_scc0 .Lat1_pairend2
; template <int TYPE>
; __device__ __forceinline__ void attn_item(const Ctx& a, int b, int h, int qt, LAS unsigned char* lds) {
;     ...
;             if (rare) {
;                 const float mnew = bump ? mref + mx : mrun;
;                 const float pre = __builtin_amdgcn_exp2f(delta);
;                 fpost = __builtin_amdgcn_exp2f(mref - mnew);
;                 mrun = mnew;
;                 lrun *= pre;
; #pragma unroll
;                 for (int db = 0; db < 2; ++db)
; #pragma unroll
;                     for (int r = 0; r < 16; ++r) oacc[db][r] *= pre;
;             }
;     ...
;         if (kp + 1 < npair) AT_STORE(bufi ^ 1);
;         __syncthreads();
	v_mov_b32 v1, v211
	s_nop 1
	v_permlane32_swap_b32 v1, v211
	v_max_f32 v1, v1, v211
	v_cmp_gt_f32 vcc, v1, v207
	s_nop 1
	v_cndmask_b32 v14, v205, v1, vcc
	v_sub_f32 v15, v205, v14
	v_exp_f32 v15, v15
	v_mov_b32 v205, v14
	v_add_f32 v207, 0x41000000, v14
	v_mul_f32 v16, v16, v15
	v_mul_f32 v17, v17, v15
	v_mul_f32 v18, v18, v15
	v_mul_f32 v19, v19, v15
	v_mul_f32 v20, v20, v15
	v_mul_f32 v21, v21, v15
	v_mul_f32 v22, v22, v15
	v_mul_f32 v23, v23, v15
	v_mul_f32 v24, v24, v15
	v_mul_f32 v25, v25, v15
	v_mul_f32 v26, v26, v15
	v_mul_f32 v27, v27, v15
	v_mul_f32 v28, v28, v15
	v_mul_f32 v29, v29, v15
	v_mul_f32 v30, v30, v15
	v_mul_f32 v31, v31, v15
	v_mul_f32 v32, v32, v15
	v_mul_f32 v33, v33, v15
	v_mul_f32 v34, v34, v15
	v_mul_f32 v35, v35, v15
	v_mul_f32 v36, v36, v15
	v_mul_f32 v37, v37, v15
	v_mul_f32 v38, v38, v15
	v_mul_f32 v39, v39, v15
	v_mul_f32 v40, v40, v15
	v_mul_f32 v41, v41, v15
	v_mul_f32 v42, v42, v15
	v_mul_f32 v43, v43, v15
	v_mul_f32 v44, v44, v15
	v_mul_f32 v45, v45, v15
	v_mul_f32 v46, v46, v15
	v_mul_f32 v47, v47, v15
	v_mul_f32 v206, v206, v15
	v_cmp_neq_f32_e64 s[36:37], 0, v205
	s_branch .Lat1_pairend2
.Lat1_skip:
	s_waitcnt lgkmcnt(0)
	s_waitcnt vmcnt(0)
	ds_write_b128 v193, v[2:5]
	ds_write_b128 v193, v[10:13] offset:9216
	ds_write_b128 v200, v[6:9]
	ds_write_b128 v200, v[136:139] offset:8192
	s_cmp_eq_u32 s13, 2
	s_cselect_b32 s8, 0x19800, 0
	s_sub_u32 s8, 0x8800, s8
	s_add_u32 s13, s13, 1
	s_cmp_eq_u32 s13, 3
	s_cselect_b32 s13, 0, s13
	s_waitcnt lgkmcnt(0)
	s_add_u32 s9, s26, 2
	s_cmp_lt_u32 s9, s30
	s_cbranch_scc0 .Lat1_mid4
	global_load_dwordx4 v[2:5], v184, s[52:53]
	global_load_dwordx4 v[6:9], v184, s[52:53] offset:1024
	global_load_dwordx4 v[10:13], v185, s[52:53]
	global_load_dwordx4 v[136:139], v185, s[52:53] offset:1024
	s_add_u32 s52, s52, 0x100000
	s_addc_u32 s53, s53, 0

; #define LAS __attribute__((address_space(3)))
; template <int TYPE>
; __device__ __forceinline__ void attn_item(const Ctx& a, int b, int h, int qt, LAS unsigned char* lds) {
;     ...
;     for (int kp = 0; kp < npair; ++kp) {
;         const int bufi = kp & 1;
;         if (kp + 1 < npair) AT_LOAD(kp + 1);
;         LAS unsigned char* Bf = lds + bufi * BUF;
;         const LAS bf16_t* Kt = (const LAS bf16_t*)Bf; const LAS bf16_t* VT = (const LAS bf16_t*)(Bf + KBYTES);
.Lat1_g1_end:
.Lat1_pairend:
	s_cmp_eq_u32 s12, 2
	s_cselect_b32 s8, 0x19800, 0
	s_sub_u32 s8, 0x8800, s8
	v_add_u32 v190, s8, v190
	v_add_u32 v191, s8, v191
	v_add_u32 v192, s8, v192
	s_add_u32 s12, s12, 1
	s_cmp_eq_u32 s12, 3
	s_cselect_b32 s12, 0, s12
	ds_read_b128 v[146:149], v190 offset:0
	ds_read_b128 v[150:153], v190 offset:4608
	ds_read_b128 v[154:157], v190 offset:32
	ds_read_b128 v[158:161], v190 offset:4640
	ds_read_b128 v[162:165], v190 offset:64
	ds_read_b128 v[166:169], v190 offset:4672

; __device__ __forceinline__ unsigned cvt_pk(float lo, float hi) { f32x2_t v = {lo, hi}; bf16x2_t b = __builtin_convertvector(v, bf16x2_t); return __builtin_bit_cast(unsigned, b); }
; template <int TYPE>
; __device__ __forceinline__ void attn_item(const Ctx& a, int b, int h, int qt, LAS unsigned char* lds) {
;     ...
;     lrun += __shfl_xor(lrun, 32);
;     const float inv = 1.f / lrun;
;     bf16_t* op = br + ((size_t)b * SEQ + qrow) * BR + (TYPE == 0 ? 0 : 1024) + h * 64;
; #pragma unroll
;     for (int db = 0; db < 2; ++db)
; #pragma unroll
;         for (int g = 0; g < 4; ++g) {
;             u32x2 w; w[0] = cvt_pk(oacc[db][g * 4 + 0] * inv, oacc[db][g * 4 + 1] * inv); w[1] = cvt_pk(oacc[db][g * 4 + 2] * inv, oacc[db][g * 4 + 3] * inv);
;             *(u32x2*)(op + db * 32 + g * 8 + hb * 4) = w;
;         }
.Lat1_epi:
	s_waitcnt lgkmcnt(0)
	v_mov_b32 v1, v206
	s_nop 1
	v_permlane32_swap_b32 v1, v206
	v_add_f32 v1, v1, v206
	v_div_scale_f32 v4, s[0:1], v1, v1, 1.0
	v_rcp_f32 v5, v4
	v_div_scale_f32 v6, vcc, 1.0, v1, 1.0
	v_fma_f32 v7, -v4, v5, 1.0
	v_fmac_f32 v5, v7, v5
	v_mul_f32 v7, v6, v5
	v_fma_f32 v8, -v4, v7, v6
	v_fmac_f32 v7, v8, v5
	v_fma_f32 v4, -v4, v7, v6
	v_div_fmas_f32 v4, v4, v5, v7
	v_div_fixup_f32 v4, v4, v1, 1.0
	v_readlane_b32 s8, v255, 7
	s_mul_i32 s8, s8, 0xc00
	s_lshl_b32 s9, s50, 7
	s_add_u32 s8, s8, s9
	s_add_u32 s8, s8, 0x800
	s_add_u32 s56, s18, s8
	s_addc_u32 s57, s19, 0
	s_movk_i32 s8, 0xc00
	v_mul_lo_u32 v181, v144, s8
	v_lshrrev_b32 v15, 5, v195
	v_lshl_add_u32 v181, v15, 3, v181
	v_mul_f32 v6, v4, v16
	v_mul_f32 v7, v4, v17
	v_mul_f32 v8, v4, v18
	v_mul_f32 v9, v4, v19
	v_cvt_pk_bf16_f32 v10, v6, v7
	v_cvt_pk_bf16_f32 v11, v8, v9
	global_store_dwordx2 v181, v[10:11], s[56:57] offset:0
	v_mul_f32 v6, v4, v20
	v_mul_f32 v7, v4, v21
	v_mul_f32 v8, v4, v22
	v_mul_f32 v9, v4, v23
	v_cvt_pk_bf16_f32 v12, v6, v7
	v_cvt_pk_bf16_f32 v13, v8, v9
	global_store_dwordx2 v181, v[12:13], s[56:57] offset:16
	v_mul_f32 v6, v4, v24
	v_mul_f32 v7, v4, v25
	v_mul_f32 v8, v4, v26
	v_mul_f32 v9, v4, v27
	v_cvt_pk_bf16_f32 v10, v6, v7
	v_cvt_pk_bf16_f32 v11, v8, v9
	global_store_dwordx2 v181, v[10:11], s[56:57] offset:32
	v_mul_f32 v6, v4, v28
	v_mul_f32 v7, v4, v29
	v_mul_f32 v8, v4, v30
	v_mul_f32 v9, v4, v31
	v_cvt_pk_bf16_f32 v12, v6, v7
	v_cvt_pk_bf16_f32 v13, v8, v9
	global_store_dwordx2 v181, v[12:13], s[56:57] offset:48
	v_mul_f32 v6, v4, v32
	v_mul_f32 v7, v4, v33
	v_mul_f32 v8, v4, v34
	v_mul_f32 v9, v4, v35
	v_cvt_pk_bf16_f32 v10, v6, v7
	v_cvt_pk_bf16_f32 v11, v8, v9
	global_store_dwordx2 v181, v[10:11], s[56:57] offset:64
	v_mul_f32 v6, v4, v36
	v_mul_f32 v7, v4, v37
	v_mul_f32 v8, v4, v38
	v_mul_f32 v9, v4, v39
	v_cvt_pk_bf16_f32 v12, v6, v7
	v_cvt_pk_bf16_f32 v13, v8, v9
	global_store_dwordx2 v181, v[12:13], s[56:57] offset:80
	v_mul_f32 v6, v4, v40
	v_mul_f32 v7, v4, v41
	v_mul_f32 v8, v4, v42
	v_mul_f32 v9, v4, v43
	v_cvt_pk_bf16_f32 v10, v6, v7
	v_cvt_pk_bf16_f32 v11, v8, v9
	global_store_dwordx2 v181, v[10:11], s[56:57] offset:96
	v_mul_f32 v6, v4, v44
	v_mul_f32 v7, v4, v45
	v_mul_f32 v8, v4, v46
	v_mul_f32 v9, v4, v47
	v_cvt_pk_bf16_f32 v12, v6, v7
	v_cvt_pk_bf16_f32 v13, v8, v9
	global_store_dwordx2 v181, v[12:13], s[56:57] offset:112
	s_barrier
	s_mov_b64 s[0:1], -1
